# v31 plus RetOut next-unit factor-table load issued at the epilogue start instead of after it behind a full drain
# speedup vs baseline: 1.0046x; 1.0046x over previous
; #define LAS __attribute__((address_space(3)))
; DI void st8(bf16_t* p, f32x4 a, f32x4 b) { u32x4 w; w.x = cvt_pk_bf16(a.x, a.y); w.y = cvt_pk_bf16(a.z, a.w); w.z = cvt_pk_bf16(b.x, b.y); w.w = cvt_pk_bf16(b.z, b.w); *(u32x4*)p = w; }
; DI void unpack8(const u32x4 w, f32x4& a, f32x4& b) { a.x = bf_lo(w.x); a.y = bf_hi(w.x); a.z = bf_lo(w.y); a.w = bf_hi(w.y); b.x = bf_lo(w.z); b.y = bf_hi(w.z); b.z = bf_lo(w.w); b.w = bf_hi(w.w); }
;     DI f32x4 factors(int row) const { const f32x4 q = *(const f32x4*)(ssqr + (size_t)row * 4);
;         const float s0 = __builtin_amdgcn_rsqf(q.x * (1.f / 256.f) + EPS), s1 = __builtin_amdgcn_rsqf(q.y * (1.f / 256.f) + EPS), s2 = __builtin_amdgcn_rsqf(q.z * (1.f / 256.f) + EPS), s3 = __builtin_amdgcn_rsqf(q.w * (1.f / 256.f) + EPS);
;         return (f32x4){s0 * __builtin_amdgcn_rcpf(s1), s1 * __builtin_amdgcn_rcpf(s2), s2 * __builtin_amdgcn_rcpf(s3), s3}; }
;     DI void prep(const Unit& u, int tid) const { if (tid < 256) *(LAS f32x4*)(tbl + (u.ui & 1) * 4096 + tid * 16) = factors(u.r0 + tid); }
;     template <int NAI> DI void run(AccRef acc, const Unit& u, int wr, int wc, int fr, int fq) const {
;         const int cl = u.pn * 256 + wc * 32 + fq * 8;
;         const LAS float* T = (const LAS float*)(tbl + (u.ui & 1) * 4096);
;         float s3v[2][4];
; #pragma unroll
;         for (int ai = 0; ai < NAI; ++ai)
; #pragma unroll
;             for (int m = 0; m < 4; ++m) s3v[ai][m] = NAI == 2 ? T[(ai * 128 + wr * 64 + m * 16 + fr) * 4 + 3] : factors(EPI_ROW(ai, m)).w;
; #pragma unroll
;         for (int ai = 0; ai < NAI; ++ai)
; #pragma unroll
;         for (int mh = 0; mh < 4; mh += 2) {
;             u32x4 gv[4][2], mv[4][2];
; #pragma unroll
;             for (int m = mh; m < mh + 2; ++m)
; #pragma unroll
;                 for (int bj = 0; bj < 2; ++bj) { const bf16_t* g = P + G_GA + (size_t)EPI_ROW(ai, m) * 1024 + cl + bj * 128; gv[m][bj] = *(const u32x4*)g; mv[m][bj] = *(const u32x4*)(g + (G_GB - G_GA)); }
; #pragma unroll
;             for (int m = mh; m < mh + 2; ++m)
; #pragma unroll
;                 for (int bj = 0; bj < 2; ++bj) { f32x4 ga, gb, ma, mb; unpack8(gv[m][bj], ga, gb); unpack8(mv[m][bj], ma, mb); const float s3 = s3v[ai][m];
;                     st8(P + G_GA + (size_t)EPI_ROW(ai, m) * 1024 + cl + bj * 128, acc[ai][bj][m][0] * s3 * ga + ma, acc[ai][bj][m][1] * s3 * gb + mb); }
;         }
;     }
.LBB0_753:
	s_and_b64 vcc, exec, s[4:5]
	s_cbranch_vccz .Lrp_skip
	v_add_u32_e32 v250, s50, v153
	v_ashrrev_i32_e32 v251, 31, v250
	v_lshl_add_u64 v[250:251], v[250:251], 4, s[94:95]
	global_load_dwordx4 v[246:249], v[250:251], off
.Lrp_skip:
	v_lshl_or_b32 v2, s52, 8, v163
	v_ashrrev_i32_e32 v3, 31, v2
	v_add_u32_e32 v142, s33, v146
	v_lshlrev_b64 v[2:3], 1, v[2:3]
	v_ashrrev_i32_e32 v143, 31, v142
	v_lshl_add_u64 v[140:141], s[16:17], 0, v[2:3]
	v_lshlrev_b64 v[144:145], 11, v[142:143]
	v_add_u32_e32 v182, 16, v142
	v_lshl_add_u64 v[180:181], v[140:141], 0, v[144:145]
	v_ashrrev_i32_e32 v183, 31, v182
	v_lshlrev_b64 v[182:183], 11, v[182:183]
	v_add_co_u32_e32 v190, vcc, s47, v180
	v_lshl_add_u64 v[198:199], v[140:141], 0, v[182:183]
	s_nop 0
	v_addc_co_u32_e32 v191, vcc, 0, v181, vcc
	global_load_dwordx4 v[168:171], v[180:181], off
	global_load_dwordx4 v[172:175], v[180:181], off offset:256
	s_nop 0
	global_load_dwordx4 v[180:183], v[198:199], off
	global_load_dwordx4 v[186:189], v[190:191], off
	s_nop 0
	global_load_dwordx4 v[190:193], v[190:191], off offset:256
	v_add_co_u32_e32 v202, vcc, s47, v198
	v_add_u32_e32 v1, s19, v151
	s_nop 0
	v_addc_co_u32_e32 v203, vcc, 0, v199, vcc
	global_load_dwordx4 v[194:197], v[202:203], off
	v_lshl_add_u64 v[200:201], s[16:17], 0, v[144:145]
	ds_read2_b32 v[206:207], v1 offset0:3 offset1:67
	v_lshl_add_u64 v[208:209], v[200:201], 0, v[2:3]
	global_load_dwordx4 v[198:201], v[198:199], off offset:256
	s_nop 0
	global_load_dwordx4 v[202:205], v[202:203], off offset:256
	v_lshl_add_u64 v[144:145], s[82:83], 0, v[144:145]
	v_lshl_add_u64 v[144:145], v[144:145], 0, v[2:3]
	s_waitcnt lgkmcnt(0)
	v_pk_mul_f32 v[130:131], v[130:131], v[206:207] op_sel_hi:[1,0]
	v_pk_mul_f32 v[128:129], v[128:129], v[206:207] op_sel_hi:[1,0]
	v_pk_mul_f32 v[126:127], v[126:127], v[206:207] op_sel_hi:[1,0]
	v_pk_mul_f32 v[124:125], v[124:125], v[206:207] op_sel_hi:[1,0]
	v_pk_mul_f32 v[122:123], v[122:123], v[206:207] op_sel_hi:[1,0]
	v_pk_mul_f32 v[120:121], v[120:121], v[206:207] op_sel_hi:[1,0]
	v_pk_mul_f32 v[118:119], v[118:119], v[206:207] op_sel_hi:[1,0]
	v_pk_mul_f32 v[116:117], v[116:117], v[206:207] op_sel_hi:[1,0]
	s_waitcnt vmcnt(0)
	v_lshlrev_b32_e32 v210, 16, v168
	v_and_b32_e32 v211, 0xffff0000, v168
	v_lshlrev_b32_e32 v168, 16, v169
	v_and_b32_e32 v169, 0xffff0000, v169
	v_lshlrev_b32_e32 v212, 16, v170
	v_and_b32_e32 v213, 0xffff0000, v170
	v_lshlrev_b32_e32 v170, 16, v171
	v_and_b32_e32 v171, 0xffff0000, v171
	v_lshlrev_b32_e32 v214, 16, v172
	v_and_b32_e32 v215, 0xffff0000, v172
	v_lshlrev_b32_e32 v172, 16, v173
	v_and_b32_e32 v173, 0xffff0000, v173
	v_lshlrev_b32_e32 v220, 16, v186
	v_and_b32_e32 v221, 0xffff0000, v186
	v_lshlrev_b32_e32 v186, 16, v187
	v_and_b32_e32 v187, 0xffff0000, v187
	v_lshlrev_b32_e32 v222, 16, v188
	v_and_b32_e32 v223, 0xffff0000, v188
	v_lshlrev_b32_e32 v188, 16, v189
	v_and_b32_e32 v189, 0xffff0000, v189
	v_lshlrev_b32_e32 v224, 16, v190
	v_and_b32_e32 v225, 0xffff0000, v190
	v_lshlrev_b32_e32 v190, 16, v191
	v_and_b32_e32 v191, 0xffff0000, v191
	v_lshlrev_b32_e32 v216, 16, v174
	v_and_b32_e32 v217, 0xffff0000, v174
	v_lshlrev_b32_e32 v174, 16, v175
	v_and_b32_e32 v175, 0xffff0000, v175
	v_lshlrev_b32_e32 v226, 16, v192
	v_and_b32_e32 v227, 0xffff0000, v192
	v_lshlrev_b32_e32 v192, 16, v193
	v_and_b32_e32 v193, 0xffff0000, v193
	v_pk_fma_f32 v[130:131], v[130:131], v[168:169], v[186:187]
	v_pk_fma_f32 v[128:129], v[128:129], v[210:211], v[220:221]
	v_pk_fma_f32 v[126:127], v[126:127], v[170:171], v[188:189]
	v_pk_fma_f32 v[124:125], v[124:125], v[212:213], v[222:223]
	v_pk_fma_f32 v[122:123], v[122:123], v[172:173], v[190:191]
	v_add_u32_e32 v172, s33, v148
	v_lshlrev_b32_e32 v218, 16, v180
	v_pk_fma_f32 v[120:121], v[120:121], v[214:215], v[224:225]
	v_pk_fma_f32 v[168:169], v[118:119], v[174:175], v[192:193]
	v_pk_fma_f32 v[170:171], v[116:117], v[216:217], v[226:227]
	v_cvt_pk_bf16_f32 v116, v128, v129
	v_cvt_pk_bf16_f32 v117, v130, v131
	v_cvt_pk_bf16_f32 v118, v124, v125
	v_cvt_pk_bf16_f32 v119, v126, v127
	v_and_b32_e32 v219, 0xffff0000, v180
	v_ashrrev_i32_e32 v173, 31, v172
	v_mov_b32_e32 v180, v207
	v_cvt_pk_bf16_f32 v120, v120, v121
	v_cvt_pk_bf16_f32 v121, v122, v123
	global_store_dwordx4 v[208:209], v[116:119], off
	v_lshlrev_b32_e32 v122, 16, v183
	v_and_b32_e32 v123, 0xffff0000, v183
	v_lshlrev_b32_e32 v116, 16, v181
	v_and_b32_e32 v117, 0xffff0000, v181
	v_lshlrev_b32_e32 v118, 16, v182
	v_and_b32_e32 v119, 0xffff0000, v182
	v_lshlrev_b32_e32 v124, 16, v194
	v_and_b32_e32 v125, 0xffff0000, v194
	v_lshlrev_b32_e32 v126, 16, v195
	v_and_b32_e32 v127, 0xffff0000, v195
	v_lshlrev_b32_e32 v128, 16, v196
	v_and_b32_e32 v129, 0xffff0000, v196
	v_lshlrev_b32_e32 v130, 16, v197
	v_and_b32_e32 v131, 0xffff0000, v197
	v_lshlrev_b64 v[172:173], 11, v[172:173]
	v_pk_mul_f32 v[114:115], v[114:115], v[180:181] op_sel_hi:[1,0]
	v_pk_mul_f32 v[112:113], v[112:113], v[180:181] op_sel_hi:[1,0]
	v_pk_mul_f32 v[110:111], v[110:111], v[180:181] op_sel_hi:[1,0]
	v_pk_mul_f32 v[108:109], v[108:109], v[180:181] op_sel_hi:[1,0]
	v_lshl_add_u64 v[174:175], s[16:17], 0, v[172:173]
	v_pk_fma_f32 v[114:115], v[114:115], v[116:117], v[126:127]
	v_pk_fma_f32 v[112:113], v[112:113], v[218:219], v[124:125]
	v_pk_fma_f32 v[116:117], v[110:111], v[122:123], v[130:131]
	v_pk_fma_f32 v[110:111], v[108:109], v[118:119], v[128:129]
	v_lshl_add_u64 v[174:175], v[174:175], 0, v[2:3]
	v_cvt_pk_bf16_f32 v108, v112, v113
	v_cvt_pk_bf16_f32 v109, v114, v115
	v_cvt_pk_bf16_f32 v110, v110, v111
	v_cvt_pk_bf16_f32 v111, v116, v117
	global_store_dwordx4 v[174:175], v[108:111], off
	v_lshlrev_b32_e32 v116, 16, v198
; DI void st8(bf16_t* p, f32x4 a, f32x4 b) { u32x4 w; w.x = cvt_pk_bf16(a.x, a.y); w.y = cvt_pk_bf16(a.z, a.w); w.z = cvt_pk_bf16(b.x, b.y); w.w = cvt_pk_bf16(b.z, b.w); *(u32x4*)p = w; }
; DI void unpack8(const u32x4 w, f32x4& a, f32x4& b) { a.x = bf_lo(w.x); a.y = bf_hi(w.x); a.z = bf_lo(w.y); a.w = bf_hi(w.y); b.x = bf_lo(w.z); b.y = bf_hi(w.z); b.z = bf_lo(w.w); b.w = bf_hi(w.w); }
;     template <int NAI> DI void run(AccRef acc, const Unit& u, int wr, int wc, int fr, int fq) const {
;     ...
;             u32x4 gv[4][2], mv[4][2];
; #pragma unroll
;             for (int m = mh; m < mh + 2; ++m)
; #pragma unroll
;                 for (int bj = 0; bj < 2; ++bj) { const bf16_t* g = P + G_GA + (size_t)EPI_ROW(ai, m) * 1024 + cl + bj * 128; gv[m][bj] = *(const u32x4*)g; mv[m][bj] = *(const u32x4*)(g + (G_GB - G_GA)); }
; #pragma unroll
;             for (int m = mh; m < mh + 2; ++m)
; #pragma unroll
;                 for (int bj = 0; bj < 2; ++bj) { f32x4 ga, gb, ma, mb; unpack8(gv[m][bj], ga, gb); unpack8(mv[m][bj], ma, mb); const float s3 = s3v[ai][m];
;                     st8(P + G_GA + (size_t)EPI_ROW(ai, m) * 1024 + cl + bj * 128, acc[ai][bj][m][0] * s3 * ga + ma, acc[ai][bj][m][1] * s3 * gb + mb); }
;         }
;     }
	v_and_b32_e32 v117, 0xffff0000, v198
	v_add_u32_e32 v108, 32, v142
	v_ashrrev_i32_e32 v109, 31, v108
	v_lshlrev_b64 v[108:109], 11, v[108:109]
	v_lshl_add_u64 v[126:127], v[140:141], 0, v[108:109]
	v_lshlrev_b32_e32 v128, 16, v202
	v_and_b32_e32 v129, 0xffff0000, v202
	v_add_co_u32_e32 v130, vcc, s47, v126
	v_lshl_add_u64 v[172:173], s[82:83], 0, v[172:173]
	v_pk_mul_f32 v[104:105], v[104:105], v[180:181] op_sel_hi:[1,0]
	v_lshlrev_b32_e32 v118, 16, v199
	v_and_b32_e32 v119, 0xffff0000, v199
	v_lshlrev_b32_e32 v122, 16, v200
	v_and_b32_e32 v123, 0xffff0000, v200
	v_lshlrev_b32_e32 v124, 16, v201
	v_and_b32_e32 v125, 0xffff0000, v201
	v_addc_co_u32_e32 v131, vcc, 0, v127, vcc
	v_lshlrev_b32_e32 v174, 16, v203
	v_and_b32_e32 v175, 0xffff0000, v203
	v_lshlrev_b32_e32 v182, 16, v204
	v_and_b32_e32 v183, 0xffff0000, v204
	v_lshlrev_b32_e32 v186, 16, v205
	v_and_b32_e32 v187, 0xffff0000, v205
	v_lshl_add_u64 v[172:173], v[172:173], 0, v[2:3]
	v_pk_mul_f32 v[106:107], v[106:107], v[180:181] op_sel_hi:[1,0]
	v_pk_fma_f32 v[104:105], v[104:105], v[116:117], v[128:129]
	v_pk_mul_f32 v[102:103], v[102:103], v[180:181] op_sel_hi:[1,0]
	v_pk_mul_f32 v[100:101], v[100:101], v[180:181] op_sel_hi:[1,0]
	v_pk_fma_f32 v[106:107], v[106:107], v[118:119], v[174:175]
	v_pk_fma_f32 v[116:117], v[102:103], v[124:125], v[186:187]
	v_pk_fma_f32 v[102:103], v[100:101], v[122:123], v[182:183]
	v_cvt_pk_bf16_f32 v100, v104, v105
	v_add_co_u32_e32 v104, vcc, s48, v172
	v_cvt_pk_bf16_f32 v101, v106, v107
	v_cvt_pk_bf16_f32 v102, v102, v103
	v_cvt_pk_bf16_f32 v103, v116, v117
	v_addc_co_u32_e32 v105, vcc, 0, v173, vcc
	global_load_dwordx4 v[108:111], v[126:127], off
	global_load_dwordx4 v[112:115], v[130:131], off
	v_cvt_pk_bf16_f32 v122, v170, v171
	global_store_dwordx4 v[104:105], v[100:103], off offset:256
	v_cvt_pk_bf16_f32 v123, v168, v169
	global_load_dwordx4 v[104:107], v[126:127], off offset:256
	v_add_co_u32_e32 v100, vcc, s48, v144
	v_add_u32_e32 v180, s33, v149
	s_nop 0
	v_addc_co_u32_e32 v101, vcc, 0, v145, vcc
	global_store_dwordx4 v[100:101], v[120:123], off offset:256
	global_load_dwordx4 v[116:119], v[130:131], off offset:256
	v_add_u32_e32 v100, 48, v142
	v_ashrrev_i32_e32 v101, 31, v100
	v_lshlrev_b64 v[100:101], 11, v[100:101]
	v_lshl_add_u64 v[100:101], v[140:141], 0, v[100:101]
	global_load_dwordx4 v[120:123], v[100:101], off
	v_add_co_u32_e32 v102, vcc, s47, v100
	ds_read2_b32 v[144:145], v1 offset0:131 offset1:195
	s_nop 0
	v_addc_co_u32_e32 v103, vcc, 0, v101, vcc
	global_load_dwordx4 v[124:127], v[102:103], off
	global_load_dwordx4 v[128:131], v[100:101], off offset:256
	s_nop 0
	global_load_dwordx4 v[100:103], v[102:103], off offset:256
	v_ashrrev_i32_e32 v181, 31, v180
	v_lshlrev_b64 v[180:181], 11, v[180:181]
	s_waitcnt lgkmcnt(0)
	v_pk_mul_f32 v[98:99], v[98:99], v[144:145] op_sel_hi:[1,0]
	v_pk_mul_f32 v[96:97], v[96:97], v[144:145] op_sel_hi:[1,0]
	v_pk_mul_f32 v[94:95], v[94:95], v[144:145] op_sel_hi:[1,0]
	v_pk_mul_f32 v[92:93], v[92:93], v[144:145] op_sel_hi:[1,0]
	v_lshl_add_u64 v[182:183], s[16:17], 0, v[180:181]
	v_lshl_add_u64 v[182:183], v[182:183], 0, v[2:3]
	v_pk_mul_f32 v[88:89], v[88:89], v[144:145] op_sel_hi:[1,0]
	v_pk_mul_f32 v[90:91], v[90:91], v[144:145] op_sel_hi:[1,0]
	v_pk_mul_f32 v[86:87], v[86:87], v[144:145] op_sel_hi:[1,0]
	v_pk_mul_f32 v[84:85], v[84:85], v[144:145] op_sel_hi:[1,0]
	v_add_u32_e32 v1, 12, v1
	s_waitcnt vmcnt(9)
	v_lshlrev_b32_e32 v168, 16, v108
	v_and_b32_e32 v169, 0xffff0000, v108
	v_lshlrev_b32_e32 v108, 16, v109
	v_and_b32_e32 v109, 0xffff0000, v109
	v_lshlrev_b32_e32 v170, 16, v110
	v_and_b32_e32 v171, 0xffff0000, v110
	v_lshlrev_b32_e32 v110, 16, v111
	v_and_b32_e32 v111, 0xffff0000, v111
	s_waitcnt vmcnt(8)
	v_lshlrev_b32_e32 v172, 16, v112
	v_and_b32_e32 v173, 0xffff0000, v112
	v_lshlrev_b32_e32 v112, 16, v113
	v_and_b32_e32 v113, 0xffff0000, v113
	v_lshlrev_b32_e32 v174, 16, v114
	v_and_b32_e32 v175, 0xffff0000, v114
	v_lshlrev_b32_e32 v114, 16, v115
	v_and_b32_e32 v115, 0xffff0000, v115
	v_pk_fma_f32 v[98:99], v[98:99], v[108:109], v[112:113]
	v_pk_fma_f32 v[96:97], v[96:97], v[168:169], v[172:173]
	v_pk_fma_f32 v[108:109], v[94:95], v[110:111], v[114:115]
	v_pk_fma_f32 v[94:95], v[92:93], v[170:171], v[174:175]
	v_cvt_pk_bf16_f32 v92, v96, v97
	v_cvt_pk_bf16_f32 v93, v98, v99
	v_cvt_pk_bf16_f32 v94, v94, v95
	v_cvt_pk_bf16_f32 v95, v108, v109
	global_store_dwordx4 v[182:183], v[92:95], off
	v_lshl_add_u64 v[112:113], s[82:83], 0, v[180:181]
	s_waitcnt vmcnt(7)
	v_lshlrev_b32_e32 v96, 16, v106
	v_lshlrev_b32_e32 v92, 16, v104
	v_and_b32_e32 v93, 0xffff0000, v104
	v_lshlrev_b32_e32 v94, 16, v105
	v_and_b32_e32 v95, 0xffff0000, v105
	s_waitcnt vmcnt(5)
	v_lshlrev_b32_e32 v104, 16, v116
	v_and_b32_e32 v105, 0xffff0000, v116
	v_and_b32_e32 v97, 0xffff0000, v106
	v_lshlrev_b32_e32 v98, 16, v107
	v_and_b32_e32 v99, 0xffff0000, v107
	v_lshlrev_b32_e32 v106, 16, v117
	v_and_b32_e32 v107, 0xffff0000, v117
	v_lshlrev_b32_e32 v108, 16, v118
	v_and_b32_e32 v109, 0xffff0000, v118
	v_lshlrev_b32_e32 v110, 16, v119
	v_and_b32_e32 v111, 0xffff0000, v119
	v_lshl_add_u64 v[112:113], v[112:113], 0, v[2:3]
	v_pk_fma_f32 v[88:89], v[88:89], v[92:93], v[104:105]
	v_pk_fma_f32 v[90:91], v[90:91], v[94:95], v[106:107]
	v_pk_fma_f32 v[92:93], v[86:87], v[98:99], v[110:111]
	v_pk_fma_f32 v[86:87], v[84:85], v[96:97], v[108:109]
	v_cvt_pk_bf16_f32 v84, v88, v89
	v_add_co_u32_e32 v88, vcc, s48, v112
	v_add_u32_e32 v104, s33, v150
	v_cvt_pk_bf16_f32 v85, v90, v91
	v_cvt_pk_bf16_f32 v86, v86, v87
	v_cvt_pk_bf16_f32 v87, v92, v93
	v_addc_co_u32_e32 v89, vcc, 0, v113, vcc
	v_ashrrev_i32_e32 v105, 31, v104
	v_mov_b32_e32 v108, v145
	global_store_dwordx4 v[88:89], v[84:87], off offset:256
	s_waitcnt vmcnt(5)
; DI void st8(bf16_t* p, f32x4 a, f32x4 b) { u32x4 w; w.x = cvt_pk_bf16(a.x, a.y); w.y = cvt_pk_bf16(a.z, a.w); w.z = cvt_pk_bf16(b.x, b.y); w.w = cvt_pk_bf16(b.z, b.w); *(u32x4*)p = w; }
; DI void unpack8(const u32x4 w, f32x4& a, f32x4& b) { a.x = bf_lo(w.x); a.y = bf_hi(w.x); a.z = bf_lo(w.y); a.w = bf_hi(w.y); b.x = bf_lo(w.z); b.y = bf_hi(w.z); b.z = bf_lo(w.w); b.w = bf_hi(w.w); }
;     template <int NAI> DI void run(AccRef acc, const Unit& u, int wr, int wc, int fr, int fq) const {
;     ...
;             u32x4 gv[4][2], mv[4][2];
; #pragma unroll
;             for (int m = mh; m < mh + 2; ++m)
; #pragma unroll
;                 for (int bj = 0; bj < 2; ++bj) { const bf16_t* g = P + G_GA + (size_t)EPI_ROW(ai, m) * 1024 + cl + bj * 128; gv[m][bj] = *(const u32x4*)g; mv[m][bj] = *(const u32x4*)(g + (G_GB - G_GA)); }
; #pragma unroll
;             for (int m = mh; m < mh + 2; ++m)
; #pragma unroll
;                 for (int bj = 0; bj < 2; ++bj) { f32x4 ga, gb, ma, mb; unpack8(gv[m][bj], ga, gb); unpack8(mv[m][bj], ma, mb); const float s3 = s3v[ai][m];
;                     st8(P + G_GA + (size_t)EPI_ROW(ai, m) * 1024 + cl + bj * 128, acc[ai][bj][m][0] * s3 * ga + ma, acc[ai][bj][m][1] * s3 * gb + mb); }
;         }
;     }
	v_lshlrev_b32_e32 v88, 16, v122
	v_and_b32_e32 v89, 0xffff0000, v122
	v_lshlrev_b32_e32 v84, 16, v120
	v_and_b32_e32 v85, 0xffff0000, v120
	v_lshlrev_b32_e32 v86, 16, v121
	v_and_b32_e32 v87, 0xffff0000, v121
	v_lshlrev_b32_e32 v90, 16, v123
	v_and_b32_e32 v91, 0xffff0000, v123
	s_waitcnt vmcnt(4)
	v_lshlrev_b32_e32 v92, 16, v124
	v_and_b32_e32 v93, 0xffff0000, v124
	v_lshlrev_b32_e32 v94, 16, v125
	v_and_b32_e32 v95, 0xffff0000, v125
	v_lshlrev_b32_e32 v96, 16, v126
	v_and_b32_e32 v97, 0xffff0000, v126
	v_lshlrev_b32_e32 v98, 16, v127
	v_and_b32_e32 v99, 0xffff0000, v127
	v_lshlrev_b64 v[104:105], 11, v[104:105]
	v_pk_mul_f32 v[82:83], v[82:83], v[108:109] op_sel_hi:[1,0]
	v_pk_mul_f32 v[80:81], v[80:81], v[108:109] op_sel_hi:[1,0]
	v_pk_mul_f32 v[78:79], v[78:79], v[108:109] op_sel_hi:[1,0]
	v_pk_mul_f32 v[76:77], v[76:77], v[108:109] op_sel_hi:[1,0]
	v_lshl_add_u64 v[106:107], s[16:17], 0, v[104:105]
	v_pk_fma_f32 v[82:83], v[82:83], v[86:87], v[94:95]
	v_pk_fma_f32 v[80:81], v[80:81], v[84:85], v[92:93]
	v_pk_fma_f32 v[84:85], v[78:79], v[90:91], v[98:99]
	v_pk_fma_f32 v[78:79], v[76:77], v[88:89], v[96:97]
	v_lshl_add_u64 v[106:107], v[106:107], 0, v[2:3]
	v_cvt_pk_bf16_f32 v76, v80, v81
	v_cvt_pk_bf16_f32 v77, v82, v83
	v_cvt_pk_bf16_f32 v78, v78, v79
	v_cvt_pk_bf16_f32 v79, v84, v85
	global_store_dwordx4 v[106:107], v[76:79], off
	s_waitcnt vmcnt(4)
	v_lshlrev_b32_e32 v84, 16, v128
	v_and_b32_e32 v85, 0xffff0000, v128
	v_add_u32_e32 v76, 0x80, v142
	v_ashrrev_i32_e32 v77, 31, v76
	v_lshlrev_b64 v[106:107], 11, v[76:77]
	v_lshl_add_u64 v[94:95], v[140:141], 0, v[106:107]
	s_waitcnt vmcnt(3)
	v_lshlrev_b32_e32 v92, 16, v100
	v_and_b32_e32 v93, 0xffff0000, v100
	v_add_co_u32_e32 v100, vcc, s47, v94
	v_lshl_add_u64 v[104:105], s[82:83], 0, v[104:105]
	v_pk_mul_f32 v[72:73], v[72:73], v[108:109] op_sel_hi:[1,0]
	v_lshlrev_b32_e32 v86, 16, v129
	v_and_b32_e32 v87, 0xffff0000, v129
	v_lshlrev_b32_e32 v88, 16, v130
	v_and_b32_e32 v89, 0xffff0000, v130
	v_lshlrev_b32_e32 v90, 16, v131
	v_and_b32_e32 v91, 0xffff0000, v131
	v_lshlrev_b32_e32 v96, 16, v101
	v_and_b32_e32 v97, 0xffff0000, v101
	v_lshlrev_b32_e32 v98, 16, v102
	v_addc_co_u32_e32 v101, vcc, 0, v95, vcc
	v_and_b32_e32 v99, 0xffff0000, v102
	v_lshlrev_b32_e32 v102, 16, v103
	v_and_b32_e32 v103, 0xffff0000, v103
	v_lshl_add_u64 v[104:105], v[104:105], 0, v[2:3]
	v_pk_mul_f32 v[74:75], v[74:75], v[108:109] op_sel_hi:[1,0]
	v_pk_fma_f32 v[72:73], v[72:73], v[84:85], v[92:93]
	v_pk_mul_f32 v[70:71], v[70:71], v[108:109] op_sel_hi:[1,0]
	v_pk_mul_f32 v[68:69], v[68:69], v[108:109] op_sel_hi:[1,0]
	v_pk_fma_f32 v[74:75], v[74:75], v[86:87], v[96:97]
	v_pk_fma_f32 v[84:85], v[70:71], v[90:91], v[102:103]
	v_pk_fma_f32 v[70:71], v[68:69], v[88:89], v[98:99]
	v_cvt_pk_bf16_f32 v68, v72, v73
	v_add_co_u32_e32 v72, vcc, s48, v104
	global_load_dwordx4 v[76:79], v[94:95], off
	global_load_dwordx4 v[80:83], v[100:101], off
	v_cvt_pk_bf16_f32 v69, v74, v75
	v_cvt_pk_bf16_f32 v70, v70, v71
	v_cvt_pk_bf16_f32 v71, v84, v85
	v_addc_co_u32_e32 v73, vcc, 0, v105, vcc
	global_store_dwordx4 v[72:73], v[68:71], off offset:256
	global_load_dwordx4 v[84:87], v[94:95], off offset:256
	global_load_dwordx4 v[88:91], v[100:101], off offset:256
	v_add_u32_e32 v68, 0x90, v142
	v_ashrrev_i32_e32 v69, 31, v68
	v_lshlrev_b64 v[74:75], 11, v[68:69]
	v_lshl_add_u64 v[68:69], v[140:141], 0, v[74:75]
	v_add_co_u32_e32 v70, vcc, s47, v68
	global_load_dwordx4 v[92:95], v[68:69], off
	s_nop 0
	v_addc_co_u32_e32 v71, vcc, 0, v69, vcc
	global_load_dwordx4 v[96:99], v[70:71], off
	ds_read2st64_b32 v[104:105], v1 offset0:8 offset1:9
	ds_read2st64_b32 v[72:73], v1 offset0:10 offset1:11
	global_load_dwordx4 v[100:103], v[68:69], off offset:256
	s_nop 0
	global_load_dwordx4 v[68:71], v[70:71], off offset:256
	v_lshl_add_u64 v[116:117], s[16:17], 0, v[106:107]
	v_lshl_add_u64 v[116:117], v[116:117], 0, v[2:3]
	s_waitcnt lgkmcnt(1)
	v_pk_mul_f32 v[66:67], v[66:67], v[104:105] op_sel_hi:[1,0]
	v_pk_mul_f32 v[64:65], v[64:65], v[104:105] op_sel_hi:[1,0]
	v_pk_mul_f32 v[62:63], v[62:63], v[104:105] op_sel_hi:[1,0]
	v_pk_mul_f32 v[60:61], v[60:61], v[104:105] op_sel_hi:[1,0]
	v_pk_mul_f32 v[56:57], v[56:57], v[104:105] op_sel_hi:[1,0]
	v_pk_mul_f32 v[58:59], v[58:59], v[104:105] op_sel_hi:[1,0]
	v_pk_mul_f32 v[54:55], v[54:55], v[104:105] op_sel_hi:[1,0]
	v_pk_mul_f32 v[52:53], v[52:53], v[104:105] op_sel_hi:[1,0]
	s_waitcnt lgkmcnt(0)
	v_pk_mul_f32 v[34:35], v[34:35], v[72:73] op_sel_hi:[1,0]
	v_pk_mul_f32 v[32:33], v[32:33], v[72:73] op_sel_hi:[1,0]
	v_pk_mul_f32 v[30:31], v[30:31], v[72:73] op_sel_hi:[1,0]
	v_pk_mul_f32 v[28:29], v[28:29], v[72:73] op_sel_hi:[1,0]
	v_pk_mul_f32 v[24:25], v[24:25], v[72:73] op_sel_hi:[1,0]
	v_pk_mul_f32 v[26:27], v[26:27], v[72:73] op_sel_hi:[1,0]
	v_pk_mul_f32 v[22:23], v[22:23], v[72:73] op_sel_hi:[1,0]
	v_pk_mul_f32 v[20:21], v[20:21], v[72:73] op_sel_hi:[1,0]
	s_waitcnt vmcnt(8)
	v_lshlrev_b32_e32 v108, 16, v76
	v_and_b32_e32 v109, 0xffff0000, v76
	v_lshlrev_b32_e32 v76, 16, v77
	v_and_b32_e32 v77, 0xffff0000, v77
	v_lshlrev_b32_e32 v110, 16, v78
	v_and_b32_e32 v111, 0xffff0000, v78
	v_lshlrev_b32_e32 v78, 16, v79
	v_and_b32_e32 v79, 0xffff0000, v79
	s_waitcnt vmcnt(7)
	v_lshlrev_b32_e32 v112, 16, v80
	v_and_b32_e32 v113, 0xffff0000, v80
	v_lshlrev_b32_e32 v80, 16, v81
	v_and_b32_e32 v81, 0xffff0000, v81
	v_lshlrev_b32_e32 v114, 16, v82
	v_and_b32_e32 v115, 0xffff0000, v82
	v_lshlrev_b32_e32 v82, 16, v83
	v_and_b32_e32 v83, 0xffff0000, v83
	v_pk_fma_f32 v[66:67], v[66:67], v[76:77], v[80:81]
	v_pk_fma_f32 v[64:65], v[64:65], v[108:109], v[112:113]
	v_pk_fma_f32 v[76:77], v[62:63], v[78:79], v[82:83]
	v_pk_fma_f32 v[62:63], v[60:61], v[110:111], v[114:115]
	v_cvt_pk_bf16_f32 v60, v64, v65
	v_cvt_pk_bf16_f32 v61, v66, v67
	v_cvt_pk_bf16_f32 v62, v62, v63
	v_cvt_pk_bf16_f32 v63, v76, v77
	global_store_dwordx4 v[116:117], v[60:63], off
	s_waitcnt vmcnt(5)
; DI void st8(bf16_t* p, f32x4 a, f32x4 b) { u32x4 w; w.x = cvt_pk_bf16(a.x, a.y); w.y = cvt_pk_bf16(a.z, a.w); w.z = cvt_pk_bf16(b.x, b.y); w.w = cvt_pk_bf16(b.z, b.w); *(u32x4*)p = w; }
; DI void unpack8(const u32x4 w, f32x4& a, f32x4& b) { a.x = bf_lo(w.x); a.y = bf_hi(w.x); a.z = bf_lo(w.y); a.w = bf_hi(w.y); b.x = bf_lo(w.z); b.y = bf_hi(w.z); b.z = bf_lo(w.w); b.w = bf_hi(w.w); }
;     template <int NAI> DI void run(AccRef acc, const Unit& u, int wr, int wc, int fr, int fq) const {
;     ...
;             u32x4 gv[4][2], mv[4][2];
; #pragma unroll
;             for (int m = mh; m < mh + 2; ++m)
; #pragma unroll
;                 for (int bj = 0; bj < 2; ++bj) { const bf16_t* g = P + G_GA + (size_t)EPI_ROW(ai, m) * 1024 + cl + bj * 128; gv[m][bj] = *(const u32x4*)g; mv[m][bj] = *(const u32x4*)(g + (G_GB - G_GA)); }
; #pragma unroll
;             for (int m = mh; m < mh + 2; ++m)
; #pragma unroll
;                 for (int bj = 0; bj < 2; ++bj) { f32x4 ga, gb, ma, mb; unpack8(gv[m][bj], ga, gb); unpack8(mv[m][bj], ma, mb); const float s3 = s3v[ai][m];
;                     st8(P + G_GA + (size_t)EPI_ROW(ai, m) * 1024 + cl + bj * 128, acc[ai][bj][m][0] * s3 * ga + ma, acc[ai][bj][m][1] * s3 * gb + mb); }
;         }
;     }
	v_lshlrev_b32_e32 v76, 16, v88
	v_and_b32_e32 v77, 0xffff0000, v88
	v_lshlrev_b32_e32 v60, 16, v84
	v_and_b32_e32 v61, 0xffff0000, v84
	v_lshlrev_b32_e32 v62, 16, v85
	v_and_b32_e32 v63, 0xffff0000, v85
	v_lshl_add_u64 v[84:85], s[82:83], 0, v[106:107]
	v_lshlrev_b32_e32 v64, 16, v86
	v_and_b32_e32 v65, 0xffff0000, v86
	v_lshlrev_b32_e32 v66, 16, v87
	v_and_b32_e32 v67, 0xffff0000, v87
	v_lshlrev_b32_e32 v78, 16, v89
	v_and_b32_e32 v79, 0xffff0000, v89
	v_lshlrev_b32_e32 v80, 16, v90
	v_and_b32_e32 v81, 0xffff0000, v90
	v_lshlrev_b32_e32 v82, 16, v91
	v_and_b32_e32 v83, 0xffff0000, v91
	v_lshl_add_u64 v[84:85], v[84:85], 0, v[2:3]
	v_pk_fma_f32 v[56:57], v[56:57], v[60:61], v[76:77]
	v_pk_fma_f32 v[58:59], v[58:59], v[62:63], v[78:79]
	v_pk_fma_f32 v[60:61], v[54:55], v[66:67], v[82:83]
	v_pk_fma_f32 v[54:55], v[52:53], v[64:65], v[80:81]
	v_cvt_pk_bf16_f32 v52, v56, v57
	v_add_co_u32_e32 v56, vcc, s48, v84
	v_cvt_pk_bf16_f32 v53, v58, v59
	v_cvt_pk_bf16_f32 v54, v54, v55
	v_cvt_pk_bf16_f32 v55, v60, v61
	v_addc_co_u32_e32 v57, vcc, 0, v85, vcc
	v_mov_b32_e32 v78, v105
	global_store_dwordx4 v[56:57], v[52:55], off offset:256
	s_waitcnt vmcnt(5)
	v_lshlrev_b32_e32 v56, 16, v94
	v_and_b32_e32 v57, 0xffff0000, v94
	v_lshlrev_b32_e32 v52, 16, v92
	v_and_b32_e32 v53, 0xffff0000, v92
	v_lshlrev_b32_e32 v54, 16, v93
	v_and_b32_e32 v55, 0xffff0000, v93
	v_lshlrev_b32_e32 v58, 16, v95
	v_and_b32_e32 v59, 0xffff0000, v95
	s_waitcnt vmcnt(4)
	v_lshlrev_b32_e32 v60, 16, v96
	v_and_b32_e32 v61, 0xffff0000, v96
	v_lshlrev_b32_e32 v62, 16, v97
	v_and_b32_e32 v63, 0xffff0000, v97
	v_lshlrev_b32_e32 v64, 16, v98
	v_and_b32_e32 v65, 0xffff0000, v98
	v_lshlrev_b32_e32 v66, 16, v99
	v_and_b32_e32 v67, 0xffff0000, v99
	v_pk_mul_f32 v[50:51], v[50:51], v[78:79] op_sel_hi:[1,0]
	v_pk_mul_f32 v[48:49], v[48:49], v[78:79] op_sel_hi:[1,0]
	v_pk_mul_f32 v[46:47], v[46:47], v[78:79] op_sel_hi:[1,0]
	v_pk_mul_f32 v[44:45], v[44:45], v[78:79] op_sel_hi:[1,0]
	v_lshl_add_u64 v[76:77], s[16:17], 0, v[74:75]
	v_pk_fma_f32 v[50:51], v[50:51], v[54:55], v[62:63]
	v_pk_fma_f32 v[48:49], v[48:49], v[52:53], v[60:61]
	v_pk_fma_f32 v[52:53], v[46:47], v[58:59], v[66:67]
	v_pk_fma_f32 v[46:47], v[44:45], v[56:57], v[64:65]
	v_lshl_add_u64 v[76:77], v[76:77], 0, v[2:3]
	v_cvt_pk_bf16_f32 v44, v48, v49
	v_cvt_pk_bf16_f32 v45, v50, v51
	v_cvt_pk_bf16_f32 v46, v46, v47
	v_cvt_pk_bf16_f32 v47, v52, v53
	global_store_dwordx4 v[76:77], v[44:47], off
	s_waitcnt vmcnt(4)
	v_lshlrev_b32_e32 v52, 16, v100
	v_and_b32_e32 v53, 0xffff0000, v100
	v_add_u32_e32 v44, 0xa0, v142
	v_ashrrev_i32_e32 v45, 31, v44
	v_lshlrev_b64 v[76:77], 11, v[44:45]
	v_lshl_add_u64 v[56:57], v[140:141], 0, v[76:77]
	v_lshlrev_b32_e32 v58, 16, v102
	v_and_b32_e32 v59, 0xffff0000, v102
	v_add_co_u32_e32 v60, vcc, s47, v56
	v_lshlrev_b32_e32 v62, 16, v103
	v_and_b32_e32 v63, 0xffff0000, v103
	s_waitcnt vmcnt(3)
	v_lshlrev_b32_e32 v64, 16, v68
	v_and_b32_e32 v65, 0xffff0000, v68
	v_lshlrev_b32_e32 v66, 16, v69
	v_and_b32_e32 v67, 0xffff0000, v69
	v_lshlrev_b32_e32 v68, 16, v70
	v_and_b32_e32 v69, 0xffff0000, v70
	v_lshlrev_b32_e32 v70, 16, v71
	v_and_b32_e32 v71, 0xffff0000, v71
	v_lshl_add_u64 v[74:75], s[82:83], 0, v[74:75]
	v_pk_mul_f32 v[40:41], v[40:41], v[78:79] op_sel_hi:[1,0]
	v_pk_mul_f32 v[38:39], v[38:39], v[78:79] op_sel_hi:[1,0]
	v_pk_mul_f32 v[36:37], v[36:37], v[78:79] op_sel_hi:[1,0]
	v_lshlrev_b32_e32 v54, 16, v101
	v_and_b32_e32 v55, 0xffff0000, v101
	v_addc_co_u32_e32 v61, vcc, 0, v57, vcc
	v_lshl_add_u64 v[74:75], v[74:75], 0, v[2:3]
	v_pk_mul_f32 v[42:43], v[42:43], v[78:79] op_sel_hi:[1,0]
	v_pk_fma_f32 v[40:41], v[40:41], v[52:53], v[64:65]
	v_pk_fma_f32 v[52:53], v[38:39], v[62:63], v[70:71]
	v_pk_fma_f32 v[38:39], v[36:37], v[58:59], v[68:69]
	global_load_dwordx4 v[44:47], v[56:57], off
	global_load_dwordx4 v[48:51], v[60:61], off
	v_pk_fma_f32 v[42:43], v[42:43], v[54:55], v[66:67]
	v_cvt_pk_bf16_f32 v38, v38, v39
	v_cvt_pk_bf16_f32 v39, v52, v53
	v_add_co_u32_e32 v52, vcc, s48, v74
	v_cvt_pk_bf16_f32 v36, v40, v41
	v_cvt_pk_bf16_f32 v37, v42, v43
	v_addc_co_u32_e32 v53, vcc, 0, v75, vcc
	global_store_dwordx4 v[52:53], v[36:39], off offset:256
	global_load_dwordx4 v[40:43], v[56:57], off offset:256
	v_add_u32_e32 v52, 0xb0, v142
	global_load_dwordx4 v[36:39], v[60:61], off offset:256
	v_ashrrev_i32_e32 v53, 31, v52
	v_lshlrev_b64 v[68:69], 11, v[52:53]
	v_lshl_add_u64 v[60:61], v[140:141], 0, v[68:69]
	global_load_dwordx4 v[52:55], v[60:61], off
	v_add_co_u32_e32 v64, vcc, s47, v60
	v_lshl_add_u64 v[82:83], s[16:17], 0, v[76:77]
	s_nop 0
	v_addc_co_u32_e32 v65, vcc, 0, v61, vcc
	global_load_dwordx4 v[56:59], v[64:65], off
	s_nop 0
	global_load_dwordx4 v[60:63], v[60:61], off offset:256
	s_nop 0
	global_load_dwordx4 v[64:67], v[64:65], off offset:256
	v_lshl_add_u64 v[82:83], v[82:83], 0, v[2:3]
	s_waitcnt vmcnt(8)
	v_lshlrev_b32_e32 v70, 16, v44
	v_and_b32_e32 v71, 0xffff0000, v44
	v_lshlrev_b32_e32 v44, 16, v45
	v_and_b32_e32 v45, 0xffff0000, v45
	v_lshlrev_b32_e32 v74, 16, v46
	v_and_b32_e32 v75, 0xffff0000, v46
	v_lshlrev_b32_e32 v46, 16, v47
	v_and_b32_e32 v47, 0xffff0000, v47
	s_waitcnt vmcnt(7)
; #define LAS __attribute__((address_space(3)))
; DI void st8(bf16_t* p, f32x4 a, f32x4 b) { u32x4 w; w.x = cvt_pk_bf16(a.x, a.y); w.y = cvt_pk_bf16(a.z, a.w); w.z = cvt_pk_bf16(b.x, b.y); w.w = cvt_pk_bf16(b.z, b.w); *(u32x4*)p = w; }
; DI void unpack8(const u32x4 w, f32x4& a, f32x4& b) { a.x = bf_lo(w.x); a.y = bf_hi(w.x); a.z = bf_lo(w.y); a.w = bf_hi(w.y); b.x = bf_lo(w.z); b.y = bf_hi(w.z); b.z = bf_lo(w.w); b.w = bf_hi(w.w); }
;     DI f32x4 factors(int row) const { const f32x4 q = *(const f32x4*)(ssqr + (size_t)row * 4);
;         const float s0 = __builtin_amdgcn_rsqf(q.x * (1.f / 256.f) + EPS), s1 = __builtin_amdgcn_rsqf(q.y * (1.f / 256.f) + EPS), s2 = __builtin_amdgcn_rsqf(q.z * (1.f / 256.f) + EPS), s3 = __builtin_amdgcn_rsqf(q.w * (1.f / 256.f) + EPS);
;         return (f32x4){s0 * __builtin_amdgcn_rcpf(s1), s1 * __builtin_amdgcn_rcpf(s2), s2 * __builtin_amdgcn_rcpf(s3), s3}; }
;     DI void prep(const Unit& u, int tid) const { if (tid < 256) *(LAS f32x4*)(tbl + (u.ui & 1) * 4096 + tid * 16) = factors(u.r0 + tid); }
;     template <int NAI> DI void run(AccRef acc, const Unit& u, int wr, int wc, int fr, int fq) const {
;     ...
;                 for (int bj = 0; bj < 2; ++bj) { const bf16_t* g = P + G_GA + (size_t)EPI_ROW(ai, m) * 1024 + cl + bj * 128; gv[m][bj] = *(const u32x4*)g; mv[m][bj] = *(const u32x4*)(g + (G_GB - G_GA)); }
; #pragma unroll
;             for (int m = mh; m < mh + 2; ++m)
; #pragma unroll
;                 for (int bj = 0; bj < 2; ++bj) { f32x4 ga, gb, ma, mb; unpack8(gv[m][bj], ga, gb); unpack8(mv[m][bj], ma, mb); const float s3 = s3v[ai][m];
;                     st8(P + G_GA + (size_t)EPI_ROW(ai, m) * 1024 + cl + bj * 128, acc[ai][bj][m][0] * s3 * ga + ma, acc[ai][bj][m][1] * s3 * gb + mb); }
	v_lshlrev_b32_e32 v78, 16, v48
	v_and_b32_e32 v79, 0xffff0000, v48
	v_lshlrev_b32_e32 v48, 16, v49
	v_and_b32_e32 v49, 0xffff0000, v49
	v_lshlrev_b32_e32 v80, 16, v50
	v_and_b32_e32 v81, 0xffff0000, v50
	v_lshlrev_b32_e32 v50, 16, v51
	v_and_b32_e32 v51, 0xffff0000, v51
	v_pk_fma_f32 v[34:35], v[34:35], v[44:45], v[48:49]
	v_pk_fma_f32 v[32:33], v[32:33], v[70:71], v[78:79]
	v_pk_fma_f32 v[44:45], v[30:31], v[46:47], v[50:51]
	v_pk_fma_f32 v[30:31], v[28:29], v[74:75], v[80:81]
	v_cvt_pk_bf16_f32 v28, v32, v33
	v_cvt_pk_bf16_f32 v29, v34, v35
	v_cvt_pk_bf16_f32 v30, v30, v31
	v_cvt_pk_bf16_f32 v31, v44, v45
	global_store_dwordx4 v[82:83], v[28:31], off
	v_lshl_add_u64 v[44:45], s[82:83], 0, v[76:77]
	s_waitcnt vmcnt(6)
	v_lshlrev_b32_e32 v32, 16, v42
	v_lshlrev_b32_e32 v28, 16, v40
	v_and_b32_e32 v29, 0xffff0000, v40
	v_lshlrev_b32_e32 v30, 16, v41
	v_and_b32_e32 v31, 0xffff0000, v41
	s_waitcnt vmcnt(5)
	v_lshlrev_b32_e32 v40, 16, v36
	v_and_b32_e32 v41, 0xffff0000, v36
	v_and_b32_e32 v33, 0xffff0000, v42
	v_lshlrev_b32_e32 v34, 16, v43
	v_and_b32_e32 v35, 0xffff0000, v43
	v_lshlrev_b32_e32 v36, 16, v37
	v_and_b32_e32 v37, 0xffff0000, v37
	v_lshlrev_b32_e32 v42, 16, v38
	v_and_b32_e32 v43, 0xffff0000, v38
	v_lshlrev_b32_e32 v38, 16, v39
	v_and_b32_e32 v39, 0xffff0000, v39
	v_lshl_add_u64 v[44:45], v[44:45], 0, v[2:3]
	v_pk_fma_f32 v[24:25], v[24:25], v[28:29], v[40:41]
	v_pk_fma_f32 v[26:27], v[26:27], v[30:31], v[36:37]
	v_pk_fma_f32 v[28:29], v[22:23], v[34:35], v[38:39]
	v_pk_fma_f32 v[22:23], v[20:21], v[32:33], v[42:43]
	v_cvt_pk_bf16_f32 v20, v24, v25
	v_add_co_u32_e32 v24, vcc, s48, v44
	v_cvt_pk_bf16_f32 v21, v26, v27
	v_cvt_pk_bf16_f32 v22, v22, v23
	v_cvt_pk_bf16_f32 v23, v28, v29
	v_addc_co_u32_e32 v25, vcc, 0, v45, vcc
	v_mov_b32_e32 v38, v73
	global_store_dwordx4 v[24:25], v[20:23], off offset:256
	s_waitcnt vmcnt(4)
	v_lshlrev_b32_e32 v28, 16, v56
	v_and_b32_e32 v29, 0xffff0000, v56
	v_lshlrev_b32_e32 v20, 16, v52
	v_and_b32_e32 v21, 0xffff0000, v52
	v_lshlrev_b32_e32 v22, 16, v53
	v_and_b32_e32 v23, 0xffff0000, v53
	v_lshlrev_b32_e32 v30, 16, v57
	v_and_b32_e32 v31, 0xffff0000, v57
	v_pk_mul_f32 v[18:19], v[18:19], v[38:39] op_sel_hi:[1,0]
	v_pk_mul_f32 v[16:17], v[16:17], v[38:39] op_sel_hi:[1,0]
	v_lshlrev_b32_e32 v24, 16, v54
	v_and_b32_e32 v25, 0xffff0000, v54
	v_lshlrev_b32_e32 v26, 16, v55
	v_and_b32_e32 v27, 0xffff0000, v55
	v_lshlrev_b32_e32 v32, 16, v58
	v_and_b32_e32 v33, 0xffff0000, v58
	v_lshlrev_b32_e32 v34, 16, v59
	v_and_b32_e32 v35, 0xffff0000, v59
	v_pk_fma_f32 v[18:19], v[18:19], v[22:23], v[30:31]
	v_pk_fma_f32 v[16:17], v[16:17], v[20:21], v[28:29]
	v_pk_mul_f32 v[14:15], v[14:15], v[38:39] op_sel_hi:[1,0]
	v_pk_mul_f32 v[12:13], v[12:13], v[38:39] op_sel_hi:[1,0]
	v_lshl_add_u64 v[36:37], s[16:17], 0, v[68:69]
	v_pk_fma_f32 v[20:21], v[14:15], v[26:27], v[34:35]
	v_pk_fma_f32 v[14:15], v[12:13], v[24:25], v[32:33]
	v_cvt_pk_bf16_f32 v12, v16, v17
	v_cvt_pk_bf16_f32 v13, v18, v19
	s_waitcnt vmcnt(3)
	v_lshlrev_b32_e32 v16, 16, v62
	v_and_b32_e32 v17, 0xffff0000, v62
	v_lshlrev_b32_e32 v18, 16, v63
	v_and_b32_e32 v19, 0xffff0000, v63
	s_waitcnt vmcnt(2)
	v_lshlrev_b32_e32 v24, 16, v66
	v_and_b32_e32 v25, 0xffff0000, v66
	v_lshlrev_b32_e32 v26, 16, v67
	v_and_b32_e32 v27, 0xffff0000, v67
	v_lshl_add_u64 v[28:29], s[82:83], 0, v[68:69]
	v_pk_mul_f32 v[6:7], v[6:7], v[38:39] op_sel_hi:[1,0]
	v_pk_mul_f32 v[4:5], v[4:5], v[38:39] op_sel_hi:[1,0]
	v_lshl_add_u64 v[36:37], v[36:37], 0, v[2:3]
	v_cvt_pk_bf16_f32 v14, v14, v15
	v_cvt_pk_bf16_f32 v15, v20, v21
	v_lshl_add_u64 v[28:29], v[28:29], 0, v[2:3]
	v_pk_fma_f32 v[6:7], v[6:7], v[18:19], v[26:27]
	v_pk_fma_f32 v[4:5], v[4:5], v[16:17], v[24:25]
	global_store_dwordx4 v[36:37], v[12:15], off
	v_lshlrev_b32_e32 v20, 16, v64
	v_and_b32_e32 v21, 0xffff0000, v64
	v_lshlrev_b32_e32 v12, 16, v60
	v_and_b32_e32 v13, 0xffff0000, v60
	v_lshlrev_b32_e32 v14, 16, v61
	v_and_b32_e32 v15, 0xffff0000, v61
	v_lshlrev_b32_e32 v22, 16, v65
	v_and_b32_e32 v23, 0xffff0000, v65
	v_pk_mul_f32 v[2:3], v[10:11], v[38:39] op_sel_hi:[1,0]
	v_pk_mul_f32 v[8:9], v[8:9], v[38:39] op_sel_hi:[1,0]
	v_cvt_pk_bf16_f32 v4, v4, v5
	v_cvt_pk_bf16_f32 v5, v6, v7
	v_add_co_u32_e32 v6, vcc, 0x2aa80000, v28
	v_pk_fma_f32 v[10:11], v[2:3], v[14:15], v[22:23]
	v_pk_fma_f32 v[2:3], v[8:9], v[12:13], v[20:21]
	v_addc_co_u32_e32 v7, vcc, 0, v29, vcc
	v_cvt_pk_bf16_f32 v2, v2, v3
	v_cvt_pk_bf16_f32 v3, v10, v11
	s_andn2_b64 vcc, exec, s[4:5]
	s_mov_b64 s[4:5], -1
	global_store_dwordx4 v[6:7], v[2:5], off offset:256
	s_cbranch_vccnz .LBB0_740
	s_and_saveexec_b64 s[4:5], s[2:3]
	s_cbranch_execz .LBB0_756
	v_mov_b32_e32 v2, v246
	v_mov_b32_e32 v3, v247
	v_mov_b32_e32 v4, v248
	v_mov_b32_e32 v5, v249
	s_lshl_b32 s19, s51, 12
	s_and_b32 s19, s19, 0x1000
	v_fmamk_f32 v1, v2, 0x3b800000, v166
	v_fmamk_f32 v2, v3, 0x3b800000, v166
	v_fmamk_f32 v4, v4, 0x3b800000, v166
	v_fmamk_f32 v5, v5, 0x3b800000, v166
	v_rsq_f32_e32 v3, v2
	v_rsq_f32_e32 v4, v4
	v_rsq_f32_e32 v5, v5
	v_rsq_f32_e32 v2, v1
	v_rcp_f32_e32 v6, v3
	v_rcp_f32_e32 v7, v4
	v_rcp_f32_e32 v1, v5
	v_pk_mul_f32 v[2:3], v[2:3], v[6:7]
	v_mul_f32_e32 v4, v4, v1
	v_add_u32_e32 v1, s19, v162
	ds_write_b128 v1, v[2:5]
